# P0: waves 4-7 run the HBM-streaming row pass before the weight transposes (waves 0-3 keep the original order) so stream and latency-bound transposes overlap per CU
# speedup vs baseline: 1.0041x; 1.0041x over previous
; #define LAS __attribute__((address_space(3)))
; __global__ void __launch_bounds__(NTHREADS, 2) mk_fwd(Args args) {
;     ...
;     if (IN(0)) {
;         LAS float* scr = (LAS float*)(lds + wave * 16384);
;         const int gw = vcu * NWAVES + wave, NGW = G * NWAVES;
;         constexpr int I_IN = (DM / 64) * (ZLD / 32), I_P = (512 / 64) * (DM / 32), I_O = (DM / 64) * (DM / 32), I_U = (DM / 64) * (FF / 32), I_D = (FF / 64) * (DM / 32);
;         constexpr int NITEMS = I_IN + 2 * I_P + I_O + I_U + I_D;
;         for (int it = gw; it < NITEMS; it += NGW) {
;             int r = it;
;             if (r < I_IN) { p0_transpose_item(w_in, DM, ZLD, Win_t, scr, r, lane); continue; } r -= I_IN;
;             if (r < I_P) { p0_transpose_item(w_pa, 512, DM, Wpa_t, scr, r, lane, nullptr, 1024, 0); continue; } r -= I_P;
;             if (r < I_P) { p0_transpose_item(w_pb, 512, DM, Wpa_t, scr, r, lane, nullptr, 1024, 512); continue; } r -= I_P;
;             if (r < I_O) { p0_transpose_item(w_out, DM, DM, Wout_t, scr, r, lane); continue; } r -= I_O;
;             if (r < I_U) { p0_transpose_item(w_up, DM, FF, Wup_t, scr, r, lane, norm_mlp); continue; } r -= I_U;
;             p0_transpose_item(w_dn, FF, DM, Wdn_t, scr, r, lane);
;         }
.LBB0_6:
	s_or_b64 exec, exec, s[4:5]
	s_add_u32 s3, s30, 0x100000
	s_addc_u32 s80, s31, 0
	s_add_u32 s68, s30, 0xa00000
	s_addc_u32 s69, s31, 0
	s_add_u32 s66, s30, 0xc00000
	s_addc_u32 s67, s31, 0
	s_add_u32 s64, s30, 0xe00000
	s_addc_u32 s65, s31, 0
	s_add_u32 s60, s30, 0x1600000
	s_addc_u32 s61, s31, 0
	s_add_u32 s62, s30, 0x2000000
	s_addc_u32 s63, s31, 0
	s_lshr_b32 s0, s16, 6
	s_cmp_lt_i32 s34, 1
	v_writelane_b32 v246, s0, 7
	s_cselect_b64 s[0:1], -1, 0
	s_cmp_gt_i32 s35, 0
	s_cselect_b64 s[4:5], -1, 0
	s_and_b64 s[16:17], s[0:1], s[4:5]
	s_andn2_b64 vcc, exec, s[16:17]
	v_and_b32_e32 v1, 63, v218
	s_cbranch_vccnz .LBB0_71
	s_lshl_b32 s0, s96, 3
	v_readlane_b32 s1, v246, 7
	s_mov_b64 s[72:73], s[92:93]
	s_add_i32 s18, s0, s1
	s_lshl_b32 s0, s33, 3
	s_mov_b64 s[74:75], s[94:95]
	s_mov_b32 s91, s96
	v_mov_b32_e32 v247, 0
	s_cmp_lt_u32 s1, 4
	s_cbranch_scc1 .Lp0_tr_entry
	v_writelane_b32 v247, 1, 10
	v_writelane_b32 v247, s18, 11
	v_writelane_b32 v247, s8, 0
	v_writelane_b32 v247, s9, 1
	v_writelane_b32 v247, s10, 2
	v_writelane_b32 v247, s11, 3
	v_writelane_b32 v247, s12, 4
	v_writelane_b32 v247, s13, 5
	v_writelane_b32 v247, s14, 6
	v_writelane_b32 v247, s15, 7
	v_writelane_b32 v247, s40, 8
	v_writelane_b32 v247, s41, 9
	s_branch .LBB0_62
.Lp0_tr_entry:
	s_cmpk_gt_i32 s18, 0x1c7f
	s_cbranch_scc1 .LBB0_62
	v_readlane_b32 s1, v246, 7
	s_lshl_b32 s1, s1, 14
	v_and_b32_e32 v4, 7, v218
	v_lshrrev_b32_e32 v20, 3, v1
	s_add_i32 s1, s1, 0
	v_lshrrev_b32_e32 v18, 5, v1
	v_mul_u32_u24_e32 v8, 0x420, v4
	v_lshlrev_b32_e32 v9, 2, v20
	s_movk_i32 s4, 0x84
	v_add3_u32 v21, s1, v8, v9
	v_or_b32_e32 v8, 2, v18
	v_mov_b32_e32 v9, 0x108
	v_mad_u32_u24 v17, v8, s4, v9
	v_mov_b32_e32 v9, 0x318
	v_and_b32_e32 v2, 31, v218
	s_cmp_lg_u64 s[10:11], 0
	v_mad_u32_u24 v37, v8, s4, v9
	v_mov_b32_e32 v9, 0x528
	v_mov_b32_e32 v3, 0
	v_lshl_add_u32 v15, v2, 2, s1
	s_cselect_b64 s[6:7], -1, 0
	v_mad_u32_u24 v28, v8, s4, v9
	v_mov_b32_e32 v9, 0x738
	v_lshlrev_b32_e32 v14, 10, v18
	v_mad_u32_u24 v19, v18, s4, v15
	v_lshlrev_b32_e32 v4, 4, v4
	v_mov_b32_e32 v5, v3
	v_writelane_b32 v246, s6, 8
	v_mul_u32_u24_e32 v16, 0x84, v8
	v_mad_u32_u24 v38, v8, s4, v9
	v_lshlrev_b32_e32 v25, 7, v20
	v_lshl_add_u64 v[6:7], s[60:61], 0, v[4:5]
	v_or_b32_e32 v22, 8, v20
	v_or_b32_e32 v23, 16, v20
	v_or_b32_e32 v24, 24, v20
	v_writelane_b32 v246, s7, 9
	v_lshl_add_u64 v[8:9], s[64:65], 0, v[4:5]
	v_lshl_add_u64 v[10:11], s[66:67], 0, v[4:5]
	v_lshl_add_u64 v[12:13], s[68:69], 0, v[4:5]
	v_lshl_or_b32 v25, s18, 12, v25
	s_lshl_b32 s1, s0, 12
	s_lshl_b32 s19, s18, 5
	s_lshl_b32 s24, s0, 5
	s_lshl_b32 s25, s18, 1
	s_lshl_b32 s26, s0, 1
	v_lshlrev_b32_e32 v26, 2, v14
	s_movk_i32 s28, 0x4000
	s_movk_i32 s29, 0x6000
	s_mov_b32 s56, 0x8000
	s_mov_b32 s57, 0xa000
	s_mov_b32 s58, 0xc000
	s_mov_b32 s59, 0xe000
	s_mov_b32 s70, 0x10000
	s_mov_b32 s71, 0x12000
	s_mov_b32 s54, 0x14000
	s_mov_b32 s55, 0x16000
	s_mov_b32 s6, 0x18000
	s_mov_b32 s7, 0x1a000
	s_mov_b32 s76, 0x1c000
	s_mov_b32 s77, 0x1e000
	s_mov_b32 s78, 0x20000
	s_mov_b32 s79, 0x22000
	s_mov_b32 s81, 0x24000
	s_mov_b32 s82, 0x26000
	s_mov_b32 s83, 0x28000
	s_mov_b32 s84, 0x2a000
	s_mov_b32 s85, 0x2c000
	s_mov_b32 s86, 0x2e000
	s_mov_b32 s87, 0x30000
	s_mov_b32 s88, 0x32000
	s_mov_b32 s89, 0x34000
	s_mov_b32 s90, 0x36000
	s_mov_b32 s27, 0x38000
	s_mov_b32 s92, 0x3a000
	s_mov_b32 s93, 0x3c000
	s_mov_b32 s94, 0x3e000
	s_mov_b32 s95, 0x88000
	s_mov_b32 s96, 0x90000
	v_add_u32_e32 v27, v15, v17
	v_add_u32_e32 v28, v15, v28
	v_lshlrev_b32_e32 v14, 2, v2
	v_add_u32_e32 v29, 0x400, v19
	v_add_u32_e32 v30, 0x800, v19
	v_add_u32_e32 v31, 0xc00, v19
	v_add_u32_e32 v32, 0x1000, v19
	v_add_u32_e32 v33, 0x1400, v19
	v_add_u32_e32 v34, 0x1800, v19
	v_add_u32_e32 v35, 0x1c00, v19
	v_add_u32_e32 v36, v15, v16
	v_add_u32_e32 v37, v15, v37
	v_add_u32_e32 v38, v15, v38
	v_mov_b32_e32 v39, 0x100
	s_mov_b32 s97, s18
	s_mov_b32 s21, 0
	s_branch .LBB0_10

; __global__ void __launch_bounds__(NTHREADS, 2) mk_fwd(Args args) {
;     ...
;         }
;         for (int i = bx * NTHREADS + tid; i < M; i += G * NTHREADS) { ss1[i] = 0.f; ss2[i] = 0.f; if (i < 256 * 16) cnt6[i] = 0u; }
;         {
;             const f32x4* gr = (const f32x4*)norm_mix + lane; f32x4 gg[4];
; #pragma unroll
;             for (int j = 0; j < 4; ++j) gg[j] = gr[64 * j];
;             for (int mrow = gw; mrow < M; mrow += 4 * NGW) {
.Lp0_done:
	s_mov_b64 s[94:95], s[74:75]
	s_mov_b64 s[92:93], s[72:73]
	s_mov_b32 s96, s91
	s_branch .LBB0_70
.LBB0_62:
	v_readlane_b32 s1, v247, 10
	s_nop 3
	s_cmp_eq_u32 s1, 2
	s_cbranch_scc1 .Lp0_done
	v_lshl_add_u32 v2, s2, 9, v218
	s_mov_b32 s1, 0x10000
	v_cmp_gt_i32_e32 vcc, s1, v2
	s_and_saveexec_b64 s[4:5], vcc
	s_cbranch_execz .LBB0_67
	s_lshl_b32 s6, s33, 9
	v_ashrrev_i32_e32 v3, 31, v2
	s_ashr_i32 s7, s6, 31
	v_lshl_add_u64 v[4:5], v[2:3], 2, s[30:31]
	s_lshl_b64 s[8:9], s[6:7], 2
	s_mov_b64 s[10:11], 0
	v_mov_b32_e32 v3, 0
	s_movk_i32 s1, 0x1000
	s_mov_b32 s7, 0xffff
	s_branch .LBB0_65

; __global__ void __launch_bounds__(NTHREADS, 2) mk_fwd(Args args) {
;     ...
;         for (int it = gw; it < NITEMS; it += NGW) {
;             int r = it;
;             if (r < I_IN) { p0_transpose_item(w_in, DM, ZLD, Win_t, scr, r, lane); continue; } r -= I_IN;
;             if (r < I_P) { p0_transpose_item(w_pa, 512, DM, Wpa_t, scr, r, lane, nullptr, 1024, 0); continue; } r -= I_P;
;             if (r < I_P) { p0_transpose_item(w_pb, 512, DM, Wpa_t, scr, r, lane, nullptr, 1024, 512); continue; } r -= I_P;
;             if (r < I_O) { p0_transpose_item(w_out, DM, DM, Wout_t, scr, r, lane); continue; } r -= I_O;
;             if (r < I_U) { p0_transpose_item(w_up, DM, FF, Wup_t, scr, r, lane, norm_mlp); continue; } r -= I_U;
;             p0_transpose_item(w_dn, FF, DM, Wdn_t, scr, r, lane);
;         }
;         for (int i = bx * NTHREADS + tid; i < M; i += G * NTHREADS) { ss1[i] = 0.f; ss2[i] = 0.f; if (i < 256 * 16) cnt6[i] = 0u; }
.LBB0_70:
	v_readlane_b32 s0, v247, 10
	s_nop 3
	s_cmp_lg_u32 s0, 1
	s_cbranch_scc1 .Lp0_end
	v_writelane_b32 v247, 2, 10
	v_readlane_b32 s8, v247, 0
	v_readlane_b32 s9, v247, 1
	v_readlane_b32 s10, v247, 2
	v_readlane_b32 s11, v247, 3
	v_readlane_b32 s12, v247, 4
	v_readlane_b32 s13, v247, 5
	v_readlane_b32 s14, v247, 6
	v_readlane_b32 s15, v247, 7
	v_readlane_b32 s40, v247, 8
	v_readlane_b32 s41, v247, 9
	v_readlane_b32 s18, v247, 11
	s_lshl_b32 s0, s33, 3
	s_nop 3
	s_branch .Lp0_tr_entry
